# no grid barrier after the last stage of the last layer (program ends there); on top of the flat-release barrier
# speedup vs baseline: 1.0009x; 1.0009x over previous
.LBB0_1114:
	v_readlane_b32 s4, v254, 63
	s_cmp_eq_u32 s4, 3
	s_cselect_b32 s4, 1, 0
	s_cmp_eq_u32 s26, 9
	s_cselect_b32 s4, s4, 0
	s_cmp_lg_u32 s4, 0
	s_cbranch_scc0 .Lbar_needed
	s_endpgm
